# attention chunk-loop items: the four Q-tile row loads issued together instead of four load/wait/LDS-write round trips
# baseline (speedup 1.0000x reference)
.Lrm_done:
	s_abs_i32 s1, s2
	v_readlane_b32 s3, v255, 12
	s_mul_hi_u32 s3, s1, s3
	v_readlane_b32 s6, v255, 11
	s_mul_i32 s4, s3, s6
	s_sub_i32 s1, s1, s4
	s_ashr_i32 s0, s2, 31
	s_add_i32 s4, s3, 1
	s_sub_i32 s5, s1, s6
	s_cmp_ge_u32 s1, s6
	s_cselect_b32 s3, s4, s3
	s_cselect_b32 s1, s5, s1
	s_add_i32 s4, s3, 1
	s_cmp_ge_u32 s1, s6
	s_cselect_b32 s1, s4, s3
	s_xor_b32 s1, s1, s0
	s_sub_i32 s7, s1, s0
	s_mul_i32 s0, s7, s6
	v_mov_b32_e32 v0, v203
	s_sub_i32 s24, s2, s0
	s_and_b32 s19, s24, 1
	v_readfirstlane_b32 s4, v0
	s_ashr_i32 s18, s4, 6
	s_and_b32 s0, s18, 3
	s_lshl_b32 s1, s19, 2
	v_and_b32_e32 v1, 63, v0
	s_or_b32 s5, s0, s1
	s_mul_i32 s0, s18, 0x1200
	s_ashr_i32 s25, s4, 8
	s_add_i32 s6, s0, 0
	v_and_b32_e32 v165, 15, v0
	v_lshlrev_b32_e32 v0, 4, v1
	v_lshrrev_b32_e32 v152, 3, v1
	s_mov_b64 s[0:1], -1
	s_cmpk_gt_i32 s24, 0x7f
	v_lshrrev_b32_e32 v166, 4, v1
	v_and_b32_e32 v130, 48, v1
	v_and_b32_e32 v8, 0x70, v0
	v_mul_u32_u24_e32 v151, 0x90, v152
	v_mul_u32_u24_e32 v150, 0x90, v165
	v_lshlrev_b32_e32 v132, 6, v165
	s_cbranch_scc0 .LBB0_229
	s_and_b32 s0, s24, 0x7fffffe
	s_add_i32 s0, s0, s25
	s_lshl_b32 s0, s0, 5
	s_lshl_b32 s1, s7, 8
	s_add_i32 s2, s0, s1
	s_addk_i32 s2, 0x7000
	v_or_b32_e32 v6, s2, v152
	v_mov_b64_e32 v[4:5], s[70:71]
	v_mad_i64_i32 v[0:1], s[0:1], v6, s77, v[4:5]
	s_lshl_b32 s26, s5, 7
	v_lshl_add_u64 v[0:1], v[0:1], 0, s[26:27]
	v_lshl_add_u64 v[0:1], v[0:1], 0, v[8:9]
	global_load_dwordx4 v[0:3], v[0:1], off offset:2048
	v_add3_u32 v7, s6, v8, v151
	s_lshl_b32 s3, s5, 6
	v_mov_b32_e32 v133, v9
	v_mov_b32_e32 v131, v9
	v_mov_b32_e32 v56, v9
	v_mov_b32_e32 v57, v9
	v_mov_b32_e32 v195, v194
	v_mov_b32_e32 v54, v9
	v_mov_b32_e32 v55, v9
	v_mov_b64_e32 v[72:73], v[56:57]
	v_mov_b64_e32 v[76:77], v[56:57]
	v_mov_b64_e32 v[80:81], v[56:57]
	v_mov_b64_e32 v[100:101], v[56:57]
	v_mov_b64_e32 v[104:105], v[56:57]
	v_mov_b64_e32 v[108:109], v[56:57]
	v_mov_b64_e32 v[112:113], v[56:57]
	v_mov_b32_e32 v140, 0
	v_mov_b64_e32 v[70:71], v[54:55]
	v_mov_b64_e32 v[74:75], v[54:55]
	v_mov_b64_e32 v[78:79], v[54:55]
	v_mov_b64_e32 v[98:99], v[54:55]
	v_mov_b64_e32 v[102:103], v[54:55]
	v_mov_b64_e32 v[106:107], v[54:55]
	v_mov_b64_e32 v[110:111], v[54:55]
	v_mov_b64_e32 v[142:143], v[194:195]
	v_mov_b32_e32 v82, 0
	v_or_b32_e32 v10, 8, v6
	v_mad_i64_i32 v[10:11], s[0:1], v10, s77, v[4:5]
	v_lshl_add_u64 v[10:11], v[10:11], 0, s[26:27]
	v_lshl_add_u64 v[10:11], v[10:11], 0, v[8:9]
	global_load_dwordx4 v[10:13], v[10:11], off offset:2048
	v_or_b32_e32 v14, 16, v6
	v_mad_i64_i32 v[14:15], s[0:1], v14, s77, v[4:5]
	v_lshl_add_u64 v[14:15], v[14:15], 0, s[26:27]
	v_lshl_add_u64 v[14:15], v[14:15], 0, v[8:9]
	global_load_dwordx4 v[14:17], v[14:15], off offset:2048
	v_or_b32_e32 v18, 24, v6
	v_mad_i64_i32 v[18:19], s[0:1], v18, s77, v[4:5]
	v_lshl_add_u64 v[18:19], v[18:19], 0, s[26:27]
	v_lshl_add_u64 v[18:19], v[18:19], 0, v[8:9]
	global_load_dwordx4 v[18:21], v[18:19], off offset:2048
	s_lshl_b32 s0, s7, 3
	s_or_b32 s0, s5, s0
	s_ashr_i32 s1, s0, 31
	s_lshl_b64 s[0:1], s[0:1], 15
	s_add_u32 s28, s69, s0
	s_addc_u32 s29, s72, s1
	s_add_u32 s0, s73, s0
	s_addc_u32 s1, s74, s1
	s_waitcnt vmcnt(3)
	ds_write_b128 v7, v[0:3] offset:34816
	s_waitcnt vmcnt(2)
	ds_write_b128 v7, v[10:13] offset:35968
	s_waitcnt vmcnt(1)
	ds_write_b128 v7, v[14:17] offset:37120
	v_add3_u32 v4, s6, v150, v130
	v_add_u32_e32 v153, 0x8800, v4
	s_waitcnt vmcnt(0)
	ds_write_b128 v7, v[18:21] offset:38272
	v_lshl_add_u64 v[2:3], s[0:1], 0, v[132:133]
	v_lshl_add_u64 v[0:1], s[28:29], 0, v[132:133]
	v_lshl_add_u64 v[136:137], v[2:3], 0, v[130:131]
	v_lshl_add_u64 v[138:139], v[0:1], 0, v[130:131]
	global_load_dwordx4 v[62:65], v[136:137], off
	global_load_dwordx4 v[58:61], v[136:137], off offset:1024
	global_load_dwordx4 v[66:69], v[136:137], off offset:2048
	global_load_dwordx4 v[50:53], v[136:137], off offset:3072
	global_load_dwordx4 v[42:45], v[138:139], off
	global_load_dwordx4 v[46:49], v[138:139], off offset:1024
	global_load_dwordx4 v[38:41], v[138:139], off offset:2048
	global_load_dwordx4 v[34:37], v[138:139], off offset:3072
	v_add_u32_e32 v131, 0x9100, v4
	s_movk_i32 s28, 0x1000
	v_mov_b64_e32 v[144:145], v[138:139]
	v_mov_b64_e32 v[146:147], v[136:137]
	s_branch .LBB0_216
